# K-loops: priority raise ahead of the barrier for all four MFMA blocks (narrow path gets its own reset), loop-back SALU in front of the loop-back barrier, B reads without post-barrier VALU address adds
# baseline (speedup 1.0000x reference)
.LBB0_318:
	ds_read_b128 v[146:149], v194
	ds_read_b128 v[150:153], v194 offset:1024
	ds_read_b128 v[154:157], v194 offset:2048
	ds_read_b128 v[158:161], v194 offset:3072
	ds_read_b128 v[130:133], v194 offset:16384
	ds_read_b128 v[134:137], v194 offset:17408
	ds_read_b128 v[138:141], v194 offset:18432
	ds_read_b128 v[142:145], v194 offset:19456
	s_add_u32 s42, s93, s9
	s_addc_u32 s43, s94, 0
	s_add_u32 s42, s42, 0xffffff80
	s_addc_u32 s43, s43, -1
	s_mov_b32 s74, m0
	s_mov_b32 m0, s65
	s_nop 0
	global_load_lds_dwordx4 v245, s[42:43]
	s_mov_b32 m0, s74
	s_nop 0
	s_mov_b32 s74, m0
	s_mov_b32 m0, s66
	s_nop 0
	global_load_lds_dwordx4 v247, s[42:43]
	s_mov_b32 m0, s74
	s_cmp_eq_u32 s57, s3
	s_cselect_b32 s73, s55, s94
	s_cselect_b32 s72, s54, s93
	s_cselect_b32 s77, s63, s92
	s_cselect_b32 s76, s62, s8
	s_waitcnt lgkmcnt(0)
	ds_read_b128 v[162:165], v252
	ds_read_b128 v[166:169], v252 offset:1024
	ds_read_b128 v[170:173], v252 offset:2048
	ds_read_b128 v[174:177], v252 offset:3072
	ds_read_b128 v[178:181], v252 offset:4096
	ds_read_b128 v[182:185], v252 offset:5120
	ds_read_b128 v[186:189], v252 offset:6144
	ds_read_b128 v[190:193], v252 offset:7168
	s_waitcnt vmcnt(8)
	s_waitcnt lgkmcnt(0)
	s_setprio 1
	s_barrier
	v_mfma_f32_16x16x32_bf16 v[124:127], v[146:149], v[162:165], v[124:127]
	v_mfma_f32_16x16x32_bf16 v[120:123], v[154:157], v[162:165], v[120:123]
	v_mfma_f32_16x16x32_bf16 v[108:111], v[146:149], v[170:173], v[108:111]
	v_mfma_f32_16x16x32_bf16 v[104:107], v[154:157], v[170:173], v[104:107]
	v_mfma_f32_16x16x32_bf16 v[92:95], v[146:149], v[178:181], v[92:95]
	v_mfma_f32_16x16x32_bf16 v[88:91], v[154:157], v[178:181], v[88:91]
	v_mfma_f32_16x16x32_bf16 v[76:79], v[146:149], v[186:189], v[76:79]
	v_mfma_f32_16x16x32_bf16 v[72:75], v[154:157], v[186:189], v[72:75]
	v_mfma_f32_16x16x32_bf16 v[124:127], v[150:153], v[166:169], v[124:127]
	v_mfma_f32_16x16x32_bf16 v[120:123], v[158:161], v[166:169], v[120:123]
	v_mfma_f32_16x16x32_bf16 v[108:111], v[150:153], v[174:177], v[108:111]
	v_mfma_f32_16x16x32_bf16 v[104:107], v[158:161], v[174:177], v[104:107]
	v_mfma_f32_16x16x32_bf16 v[92:95], v[150:153], v[182:185], v[92:95]
	v_mfma_f32_16x16x32_bf16 v[88:91], v[158:161], v[182:185], v[88:91]
	v_mfma_f32_16x16x32_bf16 v[76:79], v[150:153], v[190:193], v[76:79]
	v_mfma_f32_16x16x32_bf16 v[72:75], v[158:161], v[190:193], v[72:75]
	s_setprio 0
	s_setprio 1
	v_mfma_f32_16x16x32_bf16 v[116:119], v[130:133], v[162:165], v[116:119]
	v_mfma_f32_16x16x32_bf16 v[112:115], v[138:141], v[162:165], v[112:115]
	v_mfma_f32_16x16x32_bf16 v[100:103], v[130:133], v[170:173], v[100:103]
	v_mfma_f32_16x16x32_bf16 v[96:99], v[138:141], v[170:173], v[96:99]
	v_mfma_f32_16x16x32_bf16 v[84:87], v[130:133], v[178:181], v[84:87]
	v_mfma_f32_16x16x32_bf16 v[80:83], v[138:141], v[178:181], v[80:83]
	v_mfma_f32_16x16x32_bf16 v[68:71], v[130:133], v[186:189], v[68:71]
	v_mfma_f32_16x16x32_bf16 v[64:67], v[138:141], v[186:189], v[64:67]
	v_mfma_f32_16x16x32_bf16 v[116:119], v[134:137], v[166:169], v[116:119]
	v_mfma_f32_16x16x32_bf16 v[112:115], v[142:145], v[166:169], v[112:115]
	v_mfma_f32_16x16x32_bf16 v[100:103], v[134:137], v[174:177], v[100:103]
	v_mfma_f32_16x16x32_bf16 v[96:99], v[142:145], v[174:177], v[96:99]
	v_mfma_f32_16x16x32_bf16 v[84:87], v[134:137], v[182:185], v[84:87]
	v_mfma_f32_16x16x32_bf16 v[80:83], v[142:145], v[182:185], v[80:83]
	v_mfma_f32_16x16x32_bf16 v[68:71], v[134:137], v[190:193], v[68:71]
	v_mfma_f32_16x16x32_bf16 v[64:67], v[142:145], v[190:193], v[64:67]
	s_setprio 0
	s_barrier
	s_mov_b32 s42, m0
	s_mov_b32 m0, s14
	s_nop 0
	global_load_lds_dwordx4 v246, s[76:77]
	s_mov_b32 m0, s42
	s_add_u32 s74, s76, s9
	s_mov_b32 s42, m0
	s_mov_b32 m0, s15
	s_nop 0
	global_load_lds_dwordx4 v248, s[76:77]
	s_mov_b32 m0, s42
	s_addc_u32 s75, s77, 0
	s_mov_b32 s42, m0
	s_mov_b32 m0, s16
	s_nop 0
	global_load_lds_dwordx4 v246, s[74:75]
	s_mov_b32 m0, s42
	v_cndmask_b32_e64 v128, 0, 1, s[68:69]
	s_mov_b32 s42, m0
	s_mov_b32 m0, s17
	s_nop 0
	global_load_lds_dwordx4 v248, s[74:75]
	s_mov_b32 m0, s42
	s_andn2_b64 vcc, exec, s[68:69]
	s_mov_b32 s42, m0
	s_mov_b32 m0, s11
	s_nop 0
	global_load_lds_dwordx4 v245, s[72:73]
	s_mov_b32 m0, s42
	s_nop 0
	s_mov_b32 s42, m0
	s_mov_b32 m0, s19
	s_nop 0
	global_load_lds_dwordx4 v247, s[72:73]
	s_mov_b32 m0, s42
	ds_read_b128 v[186:189], v252 offset:16384
	ds_read_b128 v[190:193], v252 offset:17408
	ds_read_b128 v[178:181], v252 offset:18432
	ds_read_b128 v[182:185], v252 offset:19456
	ds_read_b128 v[170:173], v252 offset:20480
	ds_read_b128 v[174:177], v252 offset:21504
	ds_read_b128 v[162:165], v252 offset:22528
	ds_read_b128 v[166:169], v252 offset:23552
	v_cmp_ne_u32_e64 s[42:43], 1, v128
	s_waitcnt vmcnt(8)
	s_waitcnt lgkmcnt(0)
	s_setprio 1
	s_barrier
	s_cbranch_vccnz .Lnar_r0
	v_mfma_f32_16x16x32_bf16 v[60:63], v[146:149], v[186:189], v[60:63]
	v_mfma_f32_16x16x32_bf16 v[56:59], v[154:157], v[186:189], v[56:59]
	v_mfma_f32_16x16x32_bf16 v[44:47], v[146:149], v[178:181], v[44:47]
	v_mfma_f32_16x16x32_bf16 v[40:43], v[154:157], v[178:181], v[40:43]
	v_mfma_f32_16x16x32_bf16 v[28:31], v[146:149], v[170:173], v[28:31]
	v_mfma_f32_16x16x32_bf16 v[24:27], v[154:157], v[170:173], v[24:27]
	v_mfma_f32_16x16x32_bf16 v[12:15], v[146:149], v[162:165], v[12:15]
	v_mfma_f32_16x16x32_bf16 v[8:11], v[154:157], v[162:165], v[8:11]
	v_mfma_f32_16x16x32_bf16 v[60:63], v[150:153], v[190:193], v[60:63]
	v_mfma_f32_16x16x32_bf16 v[56:59], v[158:161], v[190:193], v[56:59]
	v_mfma_f32_16x16x32_bf16 v[44:47], v[150:153], v[182:185], v[44:47]
	v_mfma_f32_16x16x32_bf16 v[40:43], v[158:161], v[182:185], v[40:43]
	v_mfma_f32_16x16x32_bf16 v[28:31], v[150:153], v[174:177], v[28:31]
	v_mfma_f32_16x16x32_bf16 v[24:27], v[158:161], v[174:177], v[24:27]
	v_mfma_f32_16x16x32_bf16 v[12:15], v[150:153], v[166:169], v[12:15]
	v_mfma_f32_16x16x32_bf16 v[8:11], v[158:161], v[166:169], v[8:11]
	s_setprio 0
	s_setprio 1
	v_mfma_f32_16x16x32_bf16 v[52:55], v[130:133], v[186:189], v[52:55]
	v_mfma_f32_16x16x32_bf16 v[48:51], v[138:141], v[186:189], v[48:51]
	v_mfma_f32_16x16x32_bf16 v[36:39], v[130:133], v[178:181], v[36:39]
	v_mfma_f32_16x16x32_bf16 v[32:35], v[138:141], v[178:181], v[32:35]
	v_mfma_f32_16x16x32_bf16 v[20:23], v[130:133], v[170:173], v[20:23]
	v_mfma_f32_16x16x32_bf16 v[16:19], v[138:141], v[170:173], v[16:19]
	v_mfma_f32_16x16x32_bf16 v[4:7], v[130:133], v[162:165], v[4:7]
	v_mfma_f32_16x16x32_bf16 v[0:3], v[138:141], v[162:165], v[0:3]
	v_mfma_f32_16x16x32_bf16 v[52:55], v[134:137], v[190:193], v[52:55]
	v_mfma_f32_16x16x32_bf16 v[48:51], v[142:145], v[190:193], v[48:51]
	v_mfma_f32_16x16x32_bf16 v[36:39], v[134:137], v[182:185], v[36:39]
	v_mfma_f32_16x16x32_bf16 v[32:35], v[142:145], v[182:185], v[32:35]
	v_mfma_f32_16x16x32_bf16 v[20:23], v[134:137], v[174:177], v[20:23]
	v_mfma_f32_16x16x32_bf16 v[16:19], v[142:145], v[174:177], v[16:19]
	v_mfma_f32_16x16x32_bf16 v[4:7], v[134:137], v[166:169], v[4:7]
	v_mfma_f32_16x16x32_bf16 v[0:3], v[142:145], v[166:169], v[0:3]
	s_setprio 0
	s_branch .LBB0_320
.Lnar_r0:
	s_setprio 0
.LBB0_320:
	s_add_u32 s80, s72, 0x80
	s_addc_u32 s81, s73, 0
	s_add_u32 s76, s76, 0x80
	s_addc_u32 s77, s77, 0
	s_barrier
	ds_read_b128 v[146:149], v194 offset:32768
	ds_read_b128 v[150:153], v194 offset:33792
	ds_read_b128 v[154:157], v194 offset:34816
	ds_read_b128 v[158:161], v194 offset:35840
	ds_read_b128 v[130:133], v194 offset:49152
	ds_read_b128 v[134:137], v194 offset:50176
	ds_read_b128 v[138:141], v194 offset:51200
	ds_read_b128 v[142:145], v194 offset:52224
	s_add_u32 s72, s72, s9
	s_addc_u32 s73, s73, 0
	s_mov_b32 s95, m0
	s_mov_b32 m0, s20
	s_nop 0
	global_load_lds_dwordx4 v245, s[72:73]
	s_mov_b32 m0, s95
	s_nop 0
	s_mov_b32 s95, m0
	s_mov_b32 m0, s21
	s_nop 0
	global_load_lds_dwordx4 v247, s[72:73]
	s_mov_b32 m0, s95
	s_waitcnt lgkmcnt(0)
	ds_read_b128 v[162:165], v252 offset:32768
	ds_read_b128 v[166:169], v252 offset:33792
	ds_read_b128 v[170:173], v252 offset:34816
	ds_read_b128 v[174:177], v252 offset:35840
	ds_read_b128 v[178:181], v252 offset:36864
	ds_read_b128 v[182:185], v252 offset:37888
	ds_read_b128 v[186:189], v252 offset:38912
	ds_read_b128 v[190:193], v252 offset:39936
	s_waitcnt vmcnt(8)
	s_waitcnt lgkmcnt(0)
	s_setprio 1
	s_barrier
	v_mfma_f32_16x16x32_bf16 v[124:127], v[146:149], v[162:165], v[124:127]
	v_mfma_f32_16x16x32_bf16 v[120:123], v[154:157], v[162:165], v[120:123]
	v_mfma_f32_16x16x32_bf16 v[108:111], v[146:149], v[170:173], v[108:111]
	v_mfma_f32_16x16x32_bf16 v[104:107], v[154:157], v[170:173], v[104:107]
	v_mfma_f32_16x16x32_bf16 v[92:95], v[146:149], v[178:181], v[92:95]
	v_mfma_f32_16x16x32_bf16 v[88:91], v[154:157], v[178:181], v[88:91]
	v_mfma_f32_16x16x32_bf16 v[76:79], v[146:149], v[186:189], v[76:79]
	v_mfma_f32_16x16x32_bf16 v[72:75], v[154:157], v[186:189], v[72:75]
	v_mfma_f32_16x16x32_bf16 v[124:127], v[150:153], v[166:169], v[124:127]
	v_mfma_f32_16x16x32_bf16 v[120:123], v[158:161], v[166:169], v[120:123]
	v_mfma_f32_16x16x32_bf16 v[108:111], v[150:153], v[174:177], v[108:111]
	v_mfma_f32_16x16x32_bf16 v[104:107], v[158:161], v[174:177], v[104:107]
	v_mfma_f32_16x16x32_bf16 v[92:95], v[150:153], v[182:185], v[92:95]
	v_mfma_f32_16x16x32_bf16 v[88:91], v[158:161], v[182:185], v[88:91]
	v_mfma_f32_16x16x32_bf16 v[76:79], v[150:153], v[190:193], v[76:79]
	v_mfma_f32_16x16x32_bf16 v[72:75], v[158:161], v[190:193], v[72:75]
	s_setprio 0
	s_setprio 1
	v_mfma_f32_16x16x32_bf16 v[116:119], v[130:133], v[162:165], v[116:119]
	v_mfma_f32_16x16x32_bf16 v[112:115], v[138:141], v[162:165], v[112:115]
	v_mfma_f32_16x16x32_bf16 v[100:103], v[130:133], v[170:173], v[100:103]
	v_mfma_f32_16x16x32_bf16 v[96:99], v[138:141], v[170:173], v[96:99]
	v_mfma_f32_16x16x32_bf16 v[84:87], v[130:133], v[178:181], v[84:87]
	v_mfma_f32_16x16x32_bf16 v[80:83], v[138:141], v[178:181], v[80:83]
	v_mfma_f32_16x16x32_bf16 v[68:71], v[130:133], v[186:189], v[68:71]
	v_mfma_f32_16x16x32_bf16 v[64:67], v[138:141], v[186:189], v[64:67]
	v_mfma_f32_16x16x32_bf16 v[116:119], v[134:137], v[166:169], v[116:119]
	v_mfma_f32_16x16x32_bf16 v[112:115], v[142:145], v[166:169], v[112:115]
	v_mfma_f32_16x16x32_bf16 v[100:103], v[134:137], v[174:177], v[100:103]
	v_mfma_f32_16x16x32_bf16 v[96:99], v[142:145], v[174:177], v[96:99]
	v_mfma_f32_16x16x32_bf16 v[84:87], v[134:137], v[182:185], v[84:87]
	v_mfma_f32_16x16x32_bf16 v[80:83], v[142:145], v[182:185], v[80:83]
	v_mfma_f32_16x16x32_bf16 v[68:71], v[134:137], v[190:193], v[68:71]
	v_mfma_f32_16x16x32_bf16 v[64:67], v[142:145], v[190:193], v[64:67]
	s_setprio 0
	s_barrier
	s_mov_b32 s72, m0
	s_mov_b32 m0, s23
	s_nop 0
	global_load_lds_dwordx4 v246, s[76:77]
	s_mov_b32 m0, s72
	s_nop 0
	s_mov_b32 s72, m0
	s_mov_b32 m0, s30
	s_nop 0
	global_load_lds_dwordx4 v248, s[76:77]
	s_mov_b32 m0, s72
	s_add_u32 s72, s74, 0x80
	s_addc_u32 s73, s75, 0
	s_mov_b32 s74, m0
	s_mov_b32 m0, s52
	s_nop 0
	global_load_lds_dwordx4 v246, s[72:73]
	s_mov_b32 m0, s74
	s_and_b64 vcc, exec, s[42:43]
	s_mov_b32 s74, m0
	s_mov_b32 m0, s53
	s_nop 0
	global_load_lds_dwordx4 v248, s[72:73]
	s_mov_b32 m0, s74
	s_mov_b32 s72, m0
	s_mov_b32 m0, s47
	s_nop 0
	global_load_lds_dwordx4 v245, s[80:81]
	s_mov_b32 m0, s72
	s_nop 0
	s_mov_b32 s72, m0
	s_mov_b32 m0, s50
	s_nop 0
	global_load_lds_dwordx4 v247, s[80:81]
	s_mov_b32 m0, s72
	ds_read_b128 v[186:189], v252 offset:49152
	ds_read_b128 v[190:193], v252 offset:50176
	ds_read_b128 v[178:181], v252 offset:51200
	ds_read_b128 v[182:185], v252 offset:52224
	ds_read_b128 v[170:173], v252 offset:53248
	ds_read_b128 v[174:177], v252 offset:54272
	ds_read_b128 v[162:165], v252 offset:55296
	ds_read_b128 v[166:169], v252 offset:56320
	s_waitcnt vmcnt(8)
	s_waitcnt lgkmcnt(0)
	s_setprio 1
	s_barrier
	s_cbranch_vccnz .Lnar_r1
	v_mfma_f32_16x16x32_bf16 v[60:63], v[146:149], v[186:189], v[60:63]
	v_mfma_f32_16x16x32_bf16 v[56:59], v[154:157], v[186:189], v[56:59]
	v_mfma_f32_16x16x32_bf16 v[44:47], v[146:149], v[178:181], v[44:47]
	v_mfma_f32_16x16x32_bf16 v[40:43], v[154:157], v[178:181], v[40:43]
	v_mfma_f32_16x16x32_bf16 v[28:31], v[146:149], v[170:173], v[28:31]
	v_mfma_f32_16x16x32_bf16 v[24:27], v[154:157], v[170:173], v[24:27]
	v_mfma_f32_16x16x32_bf16 v[12:15], v[146:149], v[162:165], v[12:15]
	v_mfma_f32_16x16x32_bf16 v[8:11], v[154:157], v[162:165], v[8:11]
	v_mfma_f32_16x16x32_bf16 v[60:63], v[150:153], v[190:193], v[60:63]
	v_mfma_f32_16x16x32_bf16 v[56:59], v[158:161], v[190:193], v[56:59]
	v_mfma_f32_16x16x32_bf16 v[44:47], v[150:153], v[182:185], v[44:47]
	v_mfma_f32_16x16x32_bf16 v[40:43], v[158:161], v[182:185], v[40:43]
	v_mfma_f32_16x16x32_bf16 v[28:31], v[150:153], v[174:177], v[28:31]
	v_mfma_f32_16x16x32_bf16 v[24:27], v[158:161], v[174:177], v[24:27]
	v_mfma_f32_16x16x32_bf16 v[12:15], v[150:153], v[166:169], v[12:15]
	v_mfma_f32_16x16x32_bf16 v[8:11], v[158:161], v[166:169], v[8:11]
	s_setprio 0
	s_setprio 1
	v_mfma_f32_16x16x32_bf16 v[52:55], v[130:133], v[186:189], v[52:55]
	v_mfma_f32_16x16x32_bf16 v[48:51], v[138:141], v[186:189], v[48:51]
	v_mfma_f32_16x16x32_bf16 v[36:39], v[130:133], v[178:181], v[36:39]
	v_mfma_f32_16x16x32_bf16 v[32:35], v[138:141], v[178:181], v[32:35]
	v_mfma_f32_16x16x32_bf16 v[20:23], v[130:133], v[170:173], v[20:23]
	v_mfma_f32_16x16x32_bf16 v[16:19], v[138:141], v[170:173], v[16:19]
	v_mfma_f32_16x16x32_bf16 v[4:7], v[130:133], v[162:165], v[4:7]
	v_mfma_f32_16x16x32_bf16 v[0:3], v[138:141], v[162:165], v[0:3]
	v_mfma_f32_16x16x32_bf16 v[52:55], v[134:137], v[190:193], v[52:55]
	v_mfma_f32_16x16x32_bf16 v[48:51], v[142:145], v[190:193], v[48:51]
	v_mfma_f32_16x16x32_bf16 v[36:39], v[134:137], v[182:185], v[36:39]
	v_mfma_f32_16x16x32_bf16 v[32:35], v[142:145], v[182:185], v[32:35]
	v_mfma_f32_16x16x32_bf16 v[20:23], v[134:137], v[174:177], v[20:23]
	v_mfma_f32_16x16x32_bf16 v[16:19], v[142:145], v[174:177], v[16:19]
	v_mfma_f32_16x16x32_bf16 v[4:7], v[134:137], v[166:169], v[4:7]
	v_mfma_f32_16x16x32_bf16 v[0:3], v[142:145], v[166:169], v[0:3]
	s_setprio 0
	s_branch .LBB0_317
.Lnar_r1:
	s_setprio 0
	s_branch .LBB0_317

.LBB0_413:
	ds_read_b128 v[146:149], v210
	ds_read_b128 v[150:153], v210 offset:1024
	ds_read_b128 v[154:157], v210 offset:2048
	ds_read_b128 v[158:161], v210 offset:3072
	ds_read_b128 v[130:133], v210 offset:16384
	ds_read_b128 v[134:137], v210 offset:17408
	ds_read_b128 v[138:141], v210 offset:18432
	ds_read_b128 v[142:145], v210 offset:19456
	s_mov_b32 s38, m0
	s_mov_b32 m0, s30
	s_nop 0
	global_load_lds_dwordx4 v195, s[46:47]
	s_mov_b32 m0, s38
	s_nop 0
	s_mov_b32 s38, m0
	s_mov_b32 m0, s14
	s_nop 0
	global_load_lds_dwordx4 v197, s[46:47]
	s_mov_b32 m0, s38
	s_add_u32 s38, s46, 0xfffc0080
	s_addc_u32 s39, s47, -1
	s_cmp_eq_u32 s19, 12
	s_cselect_b32 s75, s27, s39
	s_cselect_b32 s74, s99, s38
	s_cselect_b32 s63, s23, s18
	s_cselect_b32 s62, s3, s8
	s_waitcnt lgkmcnt(0)
	ds_read_b128 v[162:165], v209
	ds_read_b128 v[166:169], v209 offset:1024
	ds_read_b128 v[170:173], v209 offset:2048
	ds_read_b128 v[174:177], v209 offset:3072
	ds_read_b128 v[178:181], v209 offset:4096
	ds_read_b128 v[182:185], v209 offset:5120
	ds_read_b128 v[186:189], v209 offset:6144
	ds_read_b128 v[190:193], v209 offset:7168
	s_waitcnt vmcnt(8)
	s_waitcnt lgkmcnt(0)
	s_setprio 1
	s_barrier
	v_mfma_f32_16x16x32_bf16 v[124:127], v[146:149], v[162:165], v[124:127]
	v_mfma_f32_16x16x32_bf16 v[120:123], v[154:157], v[162:165], v[120:123]
	v_mfma_f32_16x16x32_bf16 v[108:111], v[146:149], v[170:173], v[108:111]
	v_mfma_f32_16x16x32_bf16 v[104:107], v[154:157], v[170:173], v[104:107]
	v_mfma_f32_16x16x32_bf16 v[92:95], v[146:149], v[178:181], v[92:95]
	v_mfma_f32_16x16x32_bf16 v[88:91], v[154:157], v[178:181], v[88:91]
	v_mfma_f32_16x16x32_bf16 v[76:79], v[146:149], v[186:189], v[76:79]
	v_mfma_f32_16x16x32_bf16 v[72:75], v[154:157], v[186:189], v[72:75]
	v_mfma_f32_16x16x32_bf16 v[124:127], v[150:153], v[166:169], v[124:127]
	v_mfma_f32_16x16x32_bf16 v[120:123], v[158:161], v[166:169], v[120:123]
	v_mfma_f32_16x16x32_bf16 v[108:111], v[150:153], v[174:177], v[108:111]
	v_mfma_f32_16x16x32_bf16 v[104:107], v[158:161], v[174:177], v[104:107]
	v_mfma_f32_16x16x32_bf16 v[92:95], v[150:153], v[182:185], v[92:95]
	v_mfma_f32_16x16x32_bf16 v[88:91], v[158:161], v[182:185], v[88:91]
	v_mfma_f32_16x16x32_bf16 v[76:79], v[150:153], v[190:193], v[76:79]
	v_mfma_f32_16x16x32_bf16 v[72:75], v[158:161], v[190:193], v[72:75]
	s_setprio 0
	s_setprio 1
	v_mfma_f32_16x16x32_bf16 v[116:119], v[130:133], v[162:165], v[116:119]
	v_mfma_f32_16x16x32_bf16 v[112:115], v[138:141], v[162:165], v[112:115]
	v_mfma_f32_16x16x32_bf16 v[100:103], v[130:133], v[170:173], v[100:103]
	v_mfma_f32_16x16x32_bf16 v[96:99], v[138:141], v[170:173], v[96:99]
	v_mfma_f32_16x16x32_bf16 v[84:87], v[130:133], v[178:181], v[84:87]
	v_mfma_f32_16x16x32_bf16 v[80:83], v[138:141], v[178:181], v[80:83]
	v_mfma_f32_16x16x32_bf16 v[68:71], v[130:133], v[186:189], v[68:71]
	v_mfma_f32_16x16x32_bf16 v[64:67], v[138:141], v[186:189], v[64:67]
	v_mfma_f32_16x16x32_bf16 v[116:119], v[134:137], v[166:169], v[116:119]
	v_mfma_f32_16x16x32_bf16 v[112:115], v[142:145], v[166:169], v[112:115]
	v_mfma_f32_16x16x32_bf16 v[100:103], v[134:137], v[174:177], v[100:103]
	v_mfma_f32_16x16x32_bf16 v[96:99], v[142:145], v[174:177], v[96:99]
	v_mfma_f32_16x16x32_bf16 v[84:87], v[134:137], v[182:185], v[84:87]
	v_mfma_f32_16x16x32_bf16 v[80:83], v[142:145], v[182:185], v[80:83]
	v_mfma_f32_16x16x32_bf16 v[68:71], v[134:137], v[190:193], v[68:71]
	v_mfma_f32_16x16x32_bf16 v[64:67], v[142:145], v[190:193], v[64:67]
	s_setprio 0
	s_barrier
	s_mov_b32 s38, m0
	s_mov_b32 m0, s67
	s_nop 0
	global_load_lds_dwordx4 v196, s[62:63]
	s_mov_b32 m0, s38
	s_add_u32 s44, s62, 0x40000
	s_mov_b32 s38, m0
	s_mov_b32 m0, s86
	s_nop 0
	global_load_lds_dwordx4 v198, s[62:63]
	s_mov_b32 m0, s38
	s_addc_u32 s45, s63, 0
	s_mov_b32 s38, m0
	s_mov_b32 m0, s87
	s_nop 0
	global_load_lds_dwordx4 v196, s[44:45]
	s_mov_b32 m0, s38
	v_cndmask_b32_e64 v128, 0, 1, s[72:73]
	s_mov_b32 s38, m0
	s_mov_b32 m0, s88
	s_nop 0
	global_load_lds_dwordx4 v198, s[44:45]
	s_mov_b32 m0, s38
	v_cmp_ne_u32_e64 s[44:45], 1, v128
	s_mov_b32 s38, m0
	s_mov_b32 m0, s51
	s_nop 0
	global_load_lds_dwordx4 v195, s[74:75]
	s_mov_b32 m0, s38
	s_andn2_b64 vcc, exec, s[72:73]
	s_mov_b32 s38, m0
	s_mov_b32 m0, s89
	s_nop 0
	global_load_lds_dwordx4 v197, s[74:75]
	s_mov_b32 m0, s38
	ds_read_b128 v[186:189], v209 offset:16384
	ds_read_b128 v[190:193], v209 offset:17408
	ds_read_b128 v[178:181], v209 offset:18432
	ds_read_b128 v[182:185], v209 offset:19456
	ds_read_b128 v[170:173], v209 offset:20480
	ds_read_b128 v[174:177], v209 offset:21504
	ds_read_b128 v[162:165], v209 offset:22528
	ds_read_b128 v[166:169], v209 offset:23552
	s_waitcnt vmcnt(8)
	s_waitcnt lgkmcnt(0)
	s_setprio 1
	s_barrier
	s_cbranch_vccnz .Lnar_m0
	v_mfma_f32_16x16x32_bf16 v[60:63], v[146:149], v[186:189], v[60:63]
	v_mfma_f32_16x16x32_bf16 v[56:59], v[154:157], v[186:189], v[56:59]
	v_mfma_f32_16x16x32_bf16 v[44:47], v[146:149], v[178:181], v[44:47]
	v_mfma_f32_16x16x32_bf16 v[40:43], v[154:157], v[178:181], v[40:43]
	v_mfma_f32_16x16x32_bf16 v[28:31], v[146:149], v[170:173], v[28:31]
	v_mfma_f32_16x16x32_bf16 v[24:27], v[154:157], v[170:173], v[24:27]
	v_mfma_f32_16x16x32_bf16 v[12:15], v[146:149], v[162:165], v[12:15]
	v_mfma_f32_16x16x32_bf16 v[8:11], v[154:157], v[162:165], v[8:11]
	v_mfma_f32_16x16x32_bf16 v[60:63], v[150:153], v[190:193], v[60:63]
	v_mfma_f32_16x16x32_bf16 v[56:59], v[158:161], v[190:193], v[56:59]
	v_mfma_f32_16x16x32_bf16 v[44:47], v[150:153], v[182:185], v[44:47]
	v_mfma_f32_16x16x32_bf16 v[40:43], v[158:161], v[182:185], v[40:43]
	v_mfma_f32_16x16x32_bf16 v[28:31], v[150:153], v[174:177], v[28:31]
	v_mfma_f32_16x16x32_bf16 v[24:27], v[158:161], v[174:177], v[24:27]
	v_mfma_f32_16x16x32_bf16 v[12:15], v[150:153], v[166:169], v[12:15]
	v_mfma_f32_16x16x32_bf16 v[8:11], v[158:161], v[166:169], v[8:11]
	s_setprio 0
	s_setprio 1
	v_mfma_f32_16x16x32_bf16 v[52:55], v[130:133], v[186:189], v[52:55]
	v_mfma_f32_16x16x32_bf16 v[48:51], v[138:141], v[186:189], v[48:51]
	v_mfma_f32_16x16x32_bf16 v[36:39], v[130:133], v[178:181], v[36:39]
	v_mfma_f32_16x16x32_bf16 v[32:35], v[138:141], v[178:181], v[32:35]
	v_mfma_f32_16x16x32_bf16 v[20:23], v[130:133], v[170:173], v[20:23]
	v_mfma_f32_16x16x32_bf16 v[16:19], v[138:141], v[170:173], v[16:19]
	v_mfma_f32_16x16x32_bf16 v[4:7], v[130:133], v[162:165], v[4:7]
	v_mfma_f32_16x16x32_bf16 v[0:3], v[138:141], v[162:165], v[0:3]
	v_mfma_f32_16x16x32_bf16 v[52:55], v[134:137], v[190:193], v[52:55]
	v_mfma_f32_16x16x32_bf16 v[48:51], v[142:145], v[190:193], v[48:51]
	v_mfma_f32_16x16x32_bf16 v[36:39], v[134:137], v[182:185], v[36:39]
	v_mfma_f32_16x16x32_bf16 v[32:35], v[142:145], v[182:185], v[32:35]
	v_mfma_f32_16x16x32_bf16 v[20:23], v[134:137], v[174:177], v[20:23]
	v_mfma_f32_16x16x32_bf16 v[16:19], v[142:145], v[174:177], v[16:19]
	v_mfma_f32_16x16x32_bf16 v[4:7], v[134:137], v[166:169], v[4:7]
	v_mfma_f32_16x16x32_bf16 v[0:3], v[142:145], v[166:169], v[0:3]
	s_setprio 0
	s_branch .LBB0_415

.LBB0_415:
	s_add_u32 s76, s74, 0x80
	s_addc_u32 s77, s75, 0
	s_add_u32 s38, s62, 0x80
	s_addc_u32 s39, s63, 0
	s_barrier
	ds_read_b128 v[146:149], v210 offset:32768
	ds_read_b128 v[150:153], v210 offset:33792
	ds_read_b128 v[154:157], v210 offset:34816
	ds_read_b128 v[158:161], v210 offset:35840
	ds_read_b128 v[130:133], v210 offset:49152
	ds_read_b128 v[134:137], v210 offset:50176
	ds_read_b128 v[138:141], v210 offset:51200
	ds_read_b128 v[142:145], v210 offset:52224
	s_add_u32 s74, s74, 0x40000
	s_addc_u32 s75, s75, 0
	s_mov_b32 vcc_lo, m0
	s_mov_b32 m0, s92
	s_nop 0
	global_load_lds_dwordx4 v195, s[74:75]
	s_mov_b32 m0, vcc_lo
	s_nop 0
	s_mov_b32 vcc_lo, m0
	s_mov_b32 m0, s93
	s_nop 0
	global_load_lds_dwordx4 v197, s[74:75]
	s_mov_b32 m0, vcc_lo
	s_waitcnt lgkmcnt(0)
	ds_read_b128 v[162:165], v209 offset:32768
	ds_read_b128 v[166:169], v209 offset:33792
	ds_read_b128 v[170:173], v209 offset:34816
	ds_read_b128 v[174:177], v209 offset:35840
	ds_read_b128 v[178:181], v209 offset:36864
	ds_read_b128 v[182:185], v209 offset:37888
	ds_read_b128 v[186:189], v209 offset:38912
	ds_read_b128 v[190:193], v209 offset:39936
	s_waitcnt vmcnt(8)
	s_waitcnt lgkmcnt(0)
	s_setprio 1
	s_barrier
	v_mfma_f32_16x16x32_bf16 v[124:127], v[146:149], v[162:165], v[124:127]
	v_mfma_f32_16x16x32_bf16 v[120:123], v[154:157], v[162:165], v[120:123]
	v_mfma_f32_16x16x32_bf16 v[108:111], v[146:149], v[170:173], v[108:111]
	v_mfma_f32_16x16x32_bf16 v[104:107], v[154:157], v[170:173], v[104:107]
	v_mfma_f32_16x16x32_bf16 v[92:95], v[146:149], v[178:181], v[92:95]
	v_mfma_f32_16x16x32_bf16 v[88:91], v[154:157], v[178:181], v[88:91]
	v_mfma_f32_16x16x32_bf16 v[76:79], v[146:149], v[186:189], v[76:79]
	v_mfma_f32_16x16x32_bf16 v[72:75], v[154:157], v[186:189], v[72:75]
	v_mfma_f32_16x16x32_bf16 v[124:127], v[150:153], v[166:169], v[124:127]
	v_mfma_f32_16x16x32_bf16 v[120:123], v[158:161], v[166:169], v[120:123]
	v_mfma_f32_16x16x32_bf16 v[108:111], v[150:153], v[174:177], v[108:111]
	v_mfma_f32_16x16x32_bf16 v[104:107], v[158:161], v[174:177], v[104:107]
	v_mfma_f32_16x16x32_bf16 v[92:95], v[150:153], v[182:185], v[92:95]
	v_mfma_f32_16x16x32_bf16 v[88:91], v[158:161], v[182:185], v[88:91]
	v_mfma_f32_16x16x32_bf16 v[76:79], v[150:153], v[190:193], v[76:79]
	v_mfma_f32_16x16x32_bf16 v[72:75], v[158:161], v[190:193], v[72:75]
	s_setprio 0
	s_setprio 1
	v_mfma_f32_16x16x32_bf16 v[116:119], v[130:133], v[162:165], v[116:119]
	v_mfma_f32_16x16x32_bf16 v[112:115], v[138:141], v[162:165], v[112:115]
	v_mfma_f32_16x16x32_bf16 v[100:103], v[130:133], v[170:173], v[100:103]
	v_mfma_f32_16x16x32_bf16 v[96:99], v[138:141], v[170:173], v[96:99]
	v_mfma_f32_16x16x32_bf16 v[84:87], v[130:133], v[178:181], v[84:87]
	v_mfma_f32_16x16x32_bf16 v[80:83], v[138:141], v[178:181], v[80:83]
	v_mfma_f32_16x16x32_bf16 v[68:71], v[130:133], v[186:189], v[68:71]
	v_mfma_f32_16x16x32_bf16 v[64:67], v[138:141], v[186:189], v[64:67]
	v_mfma_f32_16x16x32_bf16 v[116:119], v[134:137], v[166:169], v[116:119]
	v_mfma_f32_16x16x32_bf16 v[112:115], v[142:145], v[166:169], v[112:115]
	v_mfma_f32_16x16x32_bf16 v[100:103], v[134:137], v[174:177], v[100:103]
	v_mfma_f32_16x16x32_bf16 v[96:99], v[142:145], v[174:177], v[96:99]
	v_mfma_f32_16x16x32_bf16 v[84:87], v[134:137], v[182:185], v[84:87]
	v_mfma_f32_16x16x32_bf16 v[80:83], v[142:145], v[182:185], v[80:83]
	v_mfma_f32_16x16x32_bf16 v[68:71], v[134:137], v[190:193], v[68:71]
	v_mfma_f32_16x16x32_bf16 v[64:67], v[142:145], v[190:193], v[64:67]
	s_setprio 0
	s_barrier
	s_mov_b32 s74, m0
	s_mov_b32 m0, s95
	s_nop 0
	global_load_lds_dwordx4 v196, s[38:39]
	s_mov_b32 m0, s74
	s_nop 0
	s_mov_b32 s74, m0
	s_mov_b32 m0, s96
	s_nop 0
	global_load_lds_dwordx4 v198, s[38:39]
	s_mov_b32 m0, s74
	s_add_u32 s38, s62, 0x40080
	s_addc_u32 s39, s63, 0
	s_mov_b32 s62, m0
	s_mov_b32 m0, s65
	s_nop 0
	global_load_lds_dwordx4 v196, s[38:39]
	s_mov_b32 m0, s62
	s_and_b64 vcc, exec, s[44:45]
	s_mov_b32 s62, m0
	s_mov_b32 m0, s50
	s_nop 0
	global_load_lds_dwordx4 v198, s[38:39]
	s_mov_b32 m0, s62
	s_mov_b32 s38, m0
	s_mov_b32 m0, s97
	s_nop 0
	global_load_lds_dwordx4 v195, s[76:77]
	s_mov_b32 m0, s38
	s_nop 0
	s_mov_b32 s38, m0
	s_mov_b32 m0, s9
	s_nop 0
	global_load_lds_dwordx4 v197, s[76:77]
	s_mov_b32 m0, s38
	ds_read_b128 v[186:189], v209 offset:49152
	ds_read_b128 v[190:193], v209 offset:50176
	ds_read_b128 v[178:181], v209 offset:51200
	ds_read_b128 v[182:185], v209 offset:52224
	ds_read_b128 v[170:173], v209 offset:53248
	ds_read_b128 v[174:177], v209 offset:54272
	ds_read_b128 v[162:165], v209 offset:55296
	ds_read_b128 v[166:169], v209 offset:56320
	s_waitcnt vmcnt(8)
	s_waitcnt lgkmcnt(0)
	s_setprio 1
	s_barrier
	s_cbranch_vccnz .Lnar_m1
	v_mfma_f32_16x16x32_bf16 v[60:63], v[146:149], v[186:189], v[60:63]
	v_mfma_f32_16x16x32_bf16 v[56:59], v[154:157], v[186:189], v[56:59]
	v_mfma_f32_16x16x32_bf16 v[44:47], v[146:149], v[178:181], v[44:47]
	v_mfma_f32_16x16x32_bf16 v[40:43], v[154:157], v[178:181], v[40:43]
	v_mfma_f32_16x16x32_bf16 v[28:31], v[146:149], v[170:173], v[28:31]
	v_mfma_f32_16x16x32_bf16 v[24:27], v[154:157], v[170:173], v[24:27]
	v_mfma_f32_16x16x32_bf16 v[12:15], v[146:149], v[162:165], v[12:15]
	v_mfma_f32_16x16x32_bf16 v[8:11], v[154:157], v[162:165], v[8:11]
	v_mfma_f32_16x16x32_bf16 v[60:63], v[150:153], v[190:193], v[60:63]
	v_mfma_f32_16x16x32_bf16 v[56:59], v[158:161], v[190:193], v[56:59]
	v_mfma_f32_16x16x32_bf16 v[44:47], v[150:153], v[182:185], v[44:47]
	v_mfma_f32_16x16x32_bf16 v[40:43], v[158:161], v[182:185], v[40:43]
	v_mfma_f32_16x16x32_bf16 v[28:31], v[150:153], v[174:177], v[28:31]
	v_mfma_f32_16x16x32_bf16 v[24:27], v[158:161], v[174:177], v[24:27]
	v_mfma_f32_16x16x32_bf16 v[12:15], v[150:153], v[166:169], v[12:15]
	v_mfma_f32_16x16x32_bf16 v[8:11], v[158:161], v[166:169], v[8:11]
	s_setprio 0
	s_setprio 1
	v_mfma_f32_16x16x32_bf16 v[52:55], v[130:133], v[186:189], v[52:55]
	v_mfma_f32_16x16x32_bf16 v[48:51], v[138:141], v[186:189], v[48:51]
	v_mfma_f32_16x16x32_bf16 v[36:39], v[130:133], v[178:181], v[36:39]
	v_mfma_f32_16x16x32_bf16 v[32:35], v[138:141], v[178:181], v[32:35]
	v_mfma_f32_16x16x32_bf16 v[20:23], v[130:133], v[170:173], v[20:23]
	v_mfma_f32_16x16x32_bf16 v[16:19], v[138:141], v[170:173], v[16:19]
	v_mfma_f32_16x16x32_bf16 v[4:7], v[130:133], v[162:165], v[4:7]
	v_mfma_f32_16x16x32_bf16 v[0:3], v[138:141], v[162:165], v[0:3]
	v_mfma_f32_16x16x32_bf16 v[52:55], v[134:137], v[190:193], v[52:55]
	v_mfma_f32_16x16x32_bf16 v[48:51], v[142:145], v[190:193], v[48:51]
	v_mfma_f32_16x16x32_bf16 v[36:39], v[134:137], v[182:185], v[36:39]
	v_mfma_f32_16x16x32_bf16 v[32:35], v[142:145], v[182:185], v[32:35]
	v_mfma_f32_16x16x32_bf16 v[20:23], v[134:137], v[174:177], v[20:23]
	v_mfma_f32_16x16x32_bf16 v[16:19], v[142:145], v[174:177], v[16:19]
	v_mfma_f32_16x16x32_bf16 v[4:7], v[134:137], v[166:169], v[4:7]
	v_mfma_f32_16x16x32_bf16 v[0:3], v[142:145], v[166:169], v[0:3]
	s_setprio 0
	s_branch .LBB0_412
